# barrier: invalidate before polling; out_ln rendezvous: sc1 loads of the sc1-stored partials instead of a cache invalidate
# speedup vs baseline: 1.0234x; 1.0080x over previous
.LBB0_138:
	global_load_dword v3, v145, s[42:43] sc1
	s_mov_b64 s[46:47], -1
	s_waitcnt vmcnt(0)
	v_cmp_lt_u32_e32 vcc, 7, v3
	s_cbranch_vccnz .LBB0_137
	s_cmp_lg_u32 s50, 0
	s_sleep 1
	s_cbranch_scc0 .LBB0_136
	global_load_dword v3, v145, s[42:43] sc1
	s_waitcnt vmcnt(0)
	v_cmp_gt_u32_e32 vcc, 8, v3
	s_cbranch_vccz .LBB0_137
	s_sleep 1
	global_load_dword v3, v145, s[42:43] sc1
	s_waitcnt vmcnt(0)
	v_cmp_gt_u32_e32 vcc, 8, v3
	s_cbranch_vccz .LBB0_137
	s_sleep 1
	global_load_dword v3, v145, s[42:43] sc1
	s_waitcnt vmcnt(0)
	v_cmp_gt_u32_e32 vcc, 8, v3
	s_cbranch_vccz .LBB0_137
	s_sleep 1
	global_load_dword v3, v145, s[42:43] sc1
	s_waitcnt vmcnt(0)
	v_cmp_gt_u32_e32 vcc, 8, v3
	s_cbranch_vccz .LBB0_137
	s_sleep 1
	global_load_dword v3, v145, s[42:43] sc1
	s_waitcnt vmcnt(0)
	v_cmp_gt_u32_e32 vcc, 8, v3
	s_cbranch_vccz .LBB0_137
	s_sleep 1
	global_load_dword v3, v145, s[42:43] sc1
	s_waitcnt vmcnt(0)
	v_cmp_gt_u32_e32 vcc, 8, v3
	s_cbranch_vccz .LBB0_137
	s_sleep 1
	global_load_dword v3, v145, s[42:43] sc1
	s_waitcnt vmcnt(0)
	v_cmp_gt_u32_e32 vcc, 8, v3
	s_cbranch_vccz .LBB0_137
	s_sleep 1
	s_add_i32 s50, s50, -8
	s_mov_b64 s[46:47], 0
	s_branch .LBB0_137
.LBB0_148:
	s_waitcnt vmcnt(0)
.LBB0_149:
	s_or_b64 exec, exec, s[30:31]
	s_barrier
	s_and_saveexec_b64 s[30:31], s[40:41]
	s_cbranch_execz .LBB0_39
	s_lshl_b32 s33, s33, 14
	s_add_u32 s40, s77, s33
	s_addc_u32 s41, s80, 0
	v_lshl_add_u64 v[0:1], v[0:1], 3, s[40:41]
	v_add_co_u32_e32 v4, vcc, 0x1000, v0
	s_mov_b32 s33, 0x3a800000
	s_nop 0
	v_addc_co_u32_e32 v5, vcc, 0, v1, vcc
	global_load_dwordx2 v[6:7], v[0:1], off sc1
	global_load_dwordx2 v[8:9], v[0:1], off offset:2048 sc1
	global_load_dwordx2 v[10:11], v[4:5], off sc1
	s_nop 0
	global_load_dwordx2 v[4:5], v[4:5], off offset:2048 sc1
	v_add_co_u32_e32 v12, vcc, 0x2000, v0
	v_add_u32_e32 v2, 0x24000, v2
	s_nop 0
	v_addc_co_u32_e32 v13, vcc, 0, v1, vcc
	global_load_dwordx2 v[14:15], v[12:13], off sc1
	s_nop 0
	global_load_dwordx2 v[12:13], v[12:13], off offset:2048 sc1
	v_add_co_u32_e32 v0, vcc, 0x3000, v0
	s_waitcnt vmcnt(5)
	v_add_f32_e32 v3, 0, v6
	v_addc_co_u32_e32 v1, vcc, 0, v1, vcc
	global_load_dwordx2 v[16:17], v[0:1], off sc1
	s_nop 0
	global_load_dwordx2 v[0:1], v[0:1], off offset:2048 sc1
	s_waitcnt vmcnt(6)
	v_add_f32_e32 v3, v3, v8
	v_add_f32_e32 v6, 0, v7
	s_waitcnt vmcnt(5)
	v_add_f32_e32 v3, v3, v10
	v_add_f32_e32 v6, v6, v9
	s_waitcnt vmcnt(4)
	v_add_f32_e32 v3, v3, v4
	v_add_f32_e32 v6, v6, v11
	s_waitcnt vmcnt(3)
	v_add_f32_e32 v3, v3, v14
	v_add_f32_e32 v4, v6, v5
	s_waitcnt vmcnt(2)
	v_add_f32_e32 v3, v3, v12
	v_add_f32_e32 v4, v4, v15
	v_add_f32_e32 v4, v4, v13
	s_waitcnt vmcnt(1)
	v_add_f32_e32 v3, v3, v16
	s_waitcnt vmcnt(0)
	v_add_f32_e32 v0, v3, v0
	v_add_f32_e32 v4, v4, v17
	v_mul_f32_e32 v0, 0x3a800000, v0
	v_add_f32_e32 v1, v4, v1
	v_mul_f32_e32 v3, v0, v0
	v_fma_f32 v1, v1, s33, -v3
	v_max_f32_e32 v1, 0, v1
	v_add_f32_e32 v1, 0x358637bd, v1
	s_mov_b32 s33, 0xf800000
	v_mul_f32_e32 v3, 0x4f800000, v1
	v_cmp_gt_f32_e32 vcc, s33, v1
	s_nop 1
	v_cndmask_b32_e32 v1, v1, v3, vcc
	v_sqrt_f32_e32 v3, v1
	s_nop 0
	v_add_u32_e32 v4, -1, v3
	v_add_u32_e32 v5, 1, v3
	v_fma_f32 v6, -v4, v3, v1
	v_fma_f32 v7, -v5, v3, v1
	v_cmp_ge_f32_e64 s[40:41], 0, v6
	s_nop 1
	v_cndmask_b32_e64 v3, v3, v4, s[40:41]
	v_cmp_lt_f32_e64 s[40:41], 0, v7
	s_nop 1
	v_cndmask_b32_e64 v3, v3, v5, s[40:41]
	v_mul_f32_e32 v4, 0x37800000, v3
	v_cndmask_b32_e32 v3, v3, v4, vcc
	v_cmp_class_f32_e32 vcc, v1, v157
	s_nop 1
	v_cndmask_b32_e32 v1, v3, v1, vcc
	v_div_scale_f32 v3, s[40:41], v1, v1, 1.0
	v_rcp_f32_e32 v4, v3
	v_div_scale_f32 v5, vcc, 1.0, v1, 1.0
	v_fma_f32 v6, -v3, v4, 1.0
	v_fmac_f32_e32 v4, v6, v4
	v_mul_f32_e32 v6, v5, v4
	v_fma_f32 v7, -v3, v6, v5
	v_fmac_f32_e32 v6, v7, v4
	v_fma_f32 v3, -v3, v6, v5
	v_div_fmas_f32 v3, v3, v4, v6
	v_div_fixup_f32 v1, v3, v1, 1.0
	ds_write_b64 v2, v[0:1]
	s_branch .LBB0_39

.LBB0_734:
	global_load_dword v3, v145, s[46:47] sc1
	s_mov_b64 s[50:51], -1
	s_waitcnt vmcnt(0)
	v_cmp_lt_u32_e32 vcc, 7, v3
	s_cbranch_vccnz .LBB0_733
	s_cmp_lg_u32 s58, 0
	s_sleep 1
	s_cbranch_scc0 .LBB0_732
	global_load_dword v3, v145, s[46:47] sc1
	s_waitcnt vmcnt(0)
	v_cmp_gt_u32_e32 vcc, 8, v3
	s_cbranch_vccz .LBB0_733
	s_sleep 1
	global_load_dword v3, v145, s[46:47] sc1
	s_waitcnt vmcnt(0)
	v_cmp_gt_u32_e32 vcc, 8, v3
	s_cbranch_vccz .LBB0_733
	s_sleep 1
	global_load_dword v3, v145, s[46:47] sc1
	s_waitcnt vmcnt(0)
	v_cmp_gt_u32_e32 vcc, 8, v3
	s_cbranch_vccz .LBB0_733
	s_sleep 1
	global_load_dword v3, v145, s[46:47] sc1
	s_waitcnt vmcnt(0)
	v_cmp_gt_u32_e32 vcc, 8, v3
	s_cbranch_vccz .LBB0_733
	s_sleep 1
	global_load_dword v3, v145, s[46:47] sc1
	s_waitcnt vmcnt(0)
	v_cmp_gt_u32_e32 vcc, 8, v3
	s_cbranch_vccz .LBB0_733
	s_sleep 1
	global_load_dword v3, v145, s[46:47] sc1
	s_waitcnt vmcnt(0)
	v_cmp_gt_u32_e32 vcc, 8, v3
	s_cbranch_vccz .LBB0_733
	s_sleep 1
	global_load_dword v3, v145, s[46:47] sc1
	s_waitcnt vmcnt(0)
	v_cmp_gt_u32_e32 vcc, 8, v3
	s_cbranch_vccz .LBB0_733
	s_sleep 1
	s_add_i32 s58, s58, -8
	s_mov_b64 s[50:51], 0
	s_branch .LBB0_733
.LBB0_744:
	s_waitcnt vmcnt(0)
.LBB0_745:
	s_or_b64 exec, exec, s[44:45]
	s_barrier
	s_and_saveexec_b64 s[44:45], s[40:41]
	s_cbranch_execz .LBB0_747
	s_lshl_b32 s33, s33, 14
	s_add_u32 s40, s81, s33
	s_addc_u32 s41, s84, 0
	v_lshl_add_u64 v[0:1], v[0:1], 3, s[40:41]
	v_add_co_u32_e32 v4, vcc, 0x1000, v0
	s_mov_b32 s33, 0x3a800000
	s_nop 0
	v_addc_co_u32_e32 v5, vcc, 0, v1, vcc
	global_load_dwordx2 v[6:7], v[0:1], off sc1
	global_load_dwordx2 v[8:9], v[0:1], off offset:2048 sc1
	global_load_dwordx2 v[10:11], v[4:5], off sc1
	s_nop 0
	global_load_dwordx2 v[4:5], v[4:5], off offset:2048 sc1
	v_add_co_u32_e32 v12, vcc, 0x2000, v0
	v_add_u32_e32 v2, 0x24000, v2
	s_nop 0
	v_addc_co_u32_e32 v13, vcc, 0, v1, vcc
	global_load_dwordx2 v[14:15], v[12:13], off sc1
	s_nop 0
	global_load_dwordx2 v[12:13], v[12:13], off offset:2048 sc1
	v_add_co_u32_e32 v0, vcc, 0x3000, v0
	s_waitcnt vmcnt(5)
	v_add_f32_e32 v3, 0, v6
	v_addc_co_u32_e32 v1, vcc, 0, v1, vcc
	global_load_dwordx2 v[16:17], v[0:1], off sc1
	s_nop 0
	global_load_dwordx2 v[0:1], v[0:1], off offset:2048 sc1
	s_waitcnt vmcnt(6)
	v_add_f32_e32 v3, v3, v8
	v_add_f32_e32 v6, 0, v7
	s_waitcnt vmcnt(5)
	v_add_f32_e32 v3, v3, v10
	v_add_f32_e32 v6, v6, v9
	s_waitcnt vmcnt(4)
	v_add_f32_e32 v3, v3, v4
	v_add_f32_e32 v6, v6, v11
	s_waitcnt vmcnt(3)
	v_add_f32_e32 v3, v3, v14
	v_add_f32_e32 v4, v6, v5
	s_waitcnt vmcnt(2)
	v_add_f32_e32 v3, v3, v12
	v_add_f32_e32 v4, v4, v15
	v_add_f32_e32 v4, v4, v13
	s_waitcnt vmcnt(1)
	v_add_f32_e32 v3, v3, v16
	s_waitcnt vmcnt(0)
	v_add_f32_e32 v0, v3, v0
	v_add_f32_e32 v4, v4, v17
	v_mul_f32_e32 v0, 0x3a800000, v0
	v_add_f32_e32 v1, v4, v1
	v_mul_f32_e32 v3, v0, v0
	v_fma_f32 v1, v1, s33, -v3
	v_max_f32_e32 v1, 0, v1
	v_add_f32_e32 v1, 0x358637bd, v1
	s_mov_b32 s33, 0xf800000
	v_mul_f32_e32 v3, 0x4f800000, v1
	v_cmp_gt_f32_e32 vcc, s33, v1
	s_nop 1
	v_cndmask_b32_e32 v1, v1, v3, vcc
	v_sqrt_f32_e32 v3, v1
	s_nop 0
	v_add_u32_e32 v4, -1, v3
	v_add_u32_e32 v5, 1, v3
	v_fma_f32 v6, -v4, v3, v1
	v_fma_f32 v7, -v5, v3, v1
	v_cmp_ge_f32_e64 s[40:41], 0, v6
	s_nop 1
	v_cndmask_b32_e64 v3, v3, v4, s[40:41]
	v_cmp_lt_f32_e64 s[40:41], 0, v7
	s_nop 1
	v_cndmask_b32_e64 v3, v3, v5, s[40:41]
	v_mul_f32_e32 v4, 0x37800000, v3
	v_cndmask_b32_e32 v3, v3, v4, vcc
	v_cmp_class_f32_e32 vcc, v1, v157
	s_nop 1
	v_cndmask_b32_e32 v1, v3, v1, vcc
	v_div_scale_f32 v3, s[40:41], v1, v1, 1.0
	v_rcp_f32_e32 v4, v3
	v_div_scale_f32 v5, vcc, 1.0, v1, 1.0
	v_fma_f32 v6, -v3, v4, 1.0
	v_fmac_f32_e32 v4, v6, v4
	v_mul_f32_e32 v6, v5, v4
	v_fma_f32 v7, -v3, v6, v5
	v_fmac_f32_e32 v6, v7, v4
	v_fma_f32 v3, -v3, v6, v5
	v_div_fmas_f32 v3, v3, v4, v6
	v_div_fixup_f32 v1, v3, v1, 1.0
	ds_write_b64 v2, v[0:1]

.LBB0_1058:
	global_load_dword v3, v145, s[42:43] sc1
	s_mov_b64 s[46:47], -1
	s_waitcnt vmcnt(0)
	v_cmp_lt_u32_e32 vcc, 7, v3
	s_cbranch_vccnz .LBB0_1057
	s_cmp_lg_u32 s50, 0
	s_sleep 1
	s_cbranch_scc0 .LBB0_1056
	global_load_dword v3, v145, s[42:43] sc1
	s_waitcnt vmcnt(0)
	v_cmp_gt_u32_e32 vcc, 8, v3
	s_cbranch_vccz .LBB0_1057
	s_sleep 1
	global_load_dword v3, v145, s[42:43] sc1
	s_waitcnt vmcnt(0)
	v_cmp_gt_u32_e32 vcc, 8, v3
	s_cbranch_vccz .LBB0_1057
	s_sleep 1
	global_load_dword v3, v145, s[42:43] sc1
	s_waitcnt vmcnt(0)
	v_cmp_gt_u32_e32 vcc, 8, v3
	s_cbranch_vccz .LBB0_1057
	s_sleep 1
	global_load_dword v3, v145, s[42:43] sc1
	s_waitcnt vmcnt(0)
	v_cmp_gt_u32_e32 vcc, 8, v3
	s_cbranch_vccz .LBB0_1057
	s_sleep 1
	global_load_dword v3, v145, s[42:43] sc1
	s_waitcnt vmcnt(0)
	v_cmp_gt_u32_e32 vcc, 8, v3
	s_cbranch_vccz .LBB0_1057
	s_sleep 1
	global_load_dword v3, v145, s[42:43] sc1
	s_waitcnt vmcnt(0)
	v_cmp_gt_u32_e32 vcc, 8, v3
	s_cbranch_vccz .LBB0_1057
	s_sleep 1
	global_load_dword v3, v145, s[42:43] sc1
	s_waitcnt vmcnt(0)
	v_cmp_gt_u32_e32 vcc, 8, v3
	s_cbranch_vccz .LBB0_1057
	s_sleep 1
	s_add_i32 s50, s50, -8
	s_mov_b64 s[46:47], 0
	s_branch .LBB0_1057
.LBB0_1068:
	s_waitcnt vmcnt(0)
